# st7 relu2 epilogue staged through LDS: each global store writes 8 full 128B rows instead of 32 rows x 32B
# speedup vs baseline: 1.0120x; 1.0120x over previous
.LBB0_698:
	s_or_b64 exec, exec, s[14:15]
	s_waitcnt lgkmcnt(0)
	s_barrier
	ds_read2_b32 v[136:137], v165 offset1:32
	ds_read2_b32 v[138:139], v165 offset0:64 offset1:96
	v_and_b32_e32 v140, 7, v150
	v_bfe_u32 v141, v150, 5, 1
	v_xor_b32_e32 v140, v140, v141
	v_lshlrev_b32_e32 v140, 4, v140
	v_and_b32_e32 v141, 31, v150
	v_lshrrev_b32_e32 v142, 6, v150
	v_lshlrev_b32_e32 v141, 7, v141
	v_lshl_add_u32 v141, v142, 13, v141
	v_add_u32_e32 v141, 0x10010, v141
	v_xor_b32_e32 v147, 0, v140
	v_add_u32_e32 v143, v141, v147
	v_xor_b32_e32 v147, 32, v140
	v_add_u32_e32 v144, v141, v147
	v_xor_b32_e32 v147, 64, v140
	v_add_u32_e32 v145, v141, v147
	v_xor_b32_e32 v147, 96, v140
	v_add_u32_e32 v146, v141, v147
	v_and_b32_e32 v147, 63, v150
	v_lshrrev_b32_e32 v148, 3, v147
	v_and_b32_e32 v149, 7, v147
	v_xor_b32_e32 v133, v148, v149
	v_lshlrev_b32_e32 v133, 4, v133
	v_lshl_add_u32 v133, v148, 7, v133
	v_lshl_add_u32 v133, v142, 13, v133
	v_add_u32_e32 v133, 0x10010, v133
	v_lshrrev_b32_e32 v147, 8, v150
	v_lshl_add_u32 v147, v147, 7, v148
	v_add_u32_e32 v134, s17, v147
	v_ashrrev_i32_e32 v135, 31, v134
	v_lshlrev_b64 v[134:135], 13, v[134:135]
	v_or_b32_e32 v147, s18, v163
	v_lshlrev_b32_e32 v147, 1, v147
	v_lshl_add_u32 v148, v149, 4, v147
	v_mov_b32_e32 v149, 0
	v_lshl_add_u64 v[134:135], s[8:9], 0, v[134:135]
	v_lshl_add_u64 v[134:135], v[134:135], 0, v[148:149]
	s_mov_b64 s[36:37], 0x10000
	s_nop 7
	s_waitcnt lgkmcnt(0)
	v_mul_f32_e32 v112, v112, v136
	v_mul_f32_e32 v113, v113, v136
	v_mul_f32_e32 v114, v114, v136
	v_mul_f32_e32 v115, v115, v136
	v_mul_f32_e32 v116, v116, v136
	v_mul_f32_e32 v117, v117, v136
	v_mul_f32_e32 v118, v118, v136
	v_mul_f32_e32 v119, v119, v136
	v_mul_f32_e32 v120, v120, v136
	v_mul_f32_e32 v121, v121, v136
	v_mul_f32_e32 v122, v122, v136
	v_mul_f32_e32 v123, v123, v136
	v_mul_f32_e32 v124, v124, v136
	v_mul_f32_e32 v125, v125, v136
	v_mul_f32_e32 v126, v126, v136
	v_mul_f32_e32 v127, v127, v136
	v_max_f32_e32 v112, 0, v112
	v_max_f32_e32 v113, 0, v113
	v_max_f32_e32 v114, 0, v114
	v_max_f32_e32 v115, 0, v115
	v_max_f32_e32 v116, 0, v116
	v_max_f32_e32 v117, 0, v117
	v_max_f32_e32 v118, 0, v118
	v_max_f32_e32 v119, 0, v119
	v_max_f32_e32 v120, 0, v120
	v_max_f32_e32 v121, 0, v121
	v_max_f32_e32 v122, 0, v122
	v_max_f32_e32 v123, 0, v123
	v_max_f32_e32 v124, 0, v124
	v_max_f32_e32 v125, 0, v125
	v_max_f32_e32 v126, 0, v126
	v_max_f32_e32 v127, 0, v127
	v_mul_f32_e32 v112, v112, v112
	v_mul_f32_e32 v113, v113, v113
	v_mul_f32_e32 v114, v114, v114
	v_mul_f32_e32 v115, v115, v115
	v_mul_f32_e32 v116, v116, v116
	v_mul_f32_e32 v117, v117, v117
	v_mul_f32_e32 v118, v118, v118
	v_mul_f32_e32 v119, v119, v119
	v_mul_f32_e32 v120, v120, v120
	v_mul_f32_e32 v121, v121, v121
	v_mul_f32_e32 v122, v122, v122
	v_mul_f32_e32 v123, v123, v123
	v_mul_f32_e32 v124, v124, v124
	v_mul_f32_e32 v125, v125, v125
	v_mul_f32_e32 v126, v126, v126
	v_mul_f32_e32 v127, v127, v127
	v_cvt_pk_bf16_f32 v112, v112, v113
	v_cvt_pk_bf16_f32 v113, v114, v115
	v_cvt_pk_bf16_f32 v114, v116, v117
	v_cvt_pk_bf16_f32 v115, v118, v119
	v_cvt_pk_bf16_f32 v116, v120, v121
	v_cvt_pk_bf16_f32 v117, v122, v123
	v_cvt_pk_bf16_f32 v118, v124, v125
	v_cvt_pk_bf16_f32 v119, v126, v127
	s_nop 1
	v_permlane32_swap_b32_e32 v112, v114
	v_permlane32_swap_b32_e32 v113, v115
	v_permlane32_swap_b32_e32 v116, v118
	v_permlane32_swap_b32_e32 v117, v119
	ds_write_b128 v143, v[112:115]
	ds_write_b128 v144, v[116:119]
	v_mul_f32_e32 v96, v96, v136
	v_mul_f32_e32 v97, v97, v136
	v_mul_f32_e32 v98, v98, v136
	v_mul_f32_e32 v99, v99, v136
	v_mul_f32_e32 v100, v100, v136
	v_mul_f32_e32 v101, v101, v136
	v_mul_f32_e32 v102, v102, v136
	v_mul_f32_e32 v103, v103, v136
	v_mul_f32_e32 v104, v104, v136
	v_mul_f32_e32 v105, v105, v136
	v_mul_f32_e32 v106, v106, v136
	v_mul_f32_e32 v107, v107, v136
	v_mul_f32_e32 v108, v108, v136
	v_mul_f32_e32 v109, v109, v136
	v_mul_f32_e32 v110, v110, v136
	v_mul_f32_e32 v111, v111, v136
	v_max_f32_e32 v96, 0, v96
	v_max_f32_e32 v97, 0, v97
	v_max_f32_e32 v98, 0, v98
	v_max_f32_e32 v99, 0, v99
	v_max_f32_e32 v100, 0, v100
	v_max_f32_e32 v101, 0, v101
	v_max_f32_e32 v102, 0, v102
	v_max_f32_e32 v103, 0, v103
	v_max_f32_e32 v104, 0, v104
	v_max_f32_e32 v105, 0, v105
	v_max_f32_e32 v106, 0, v106
	v_max_f32_e32 v107, 0, v107
	v_max_f32_e32 v108, 0, v108
	v_max_f32_e32 v109, 0, v109
	v_max_f32_e32 v110, 0, v110
	v_max_f32_e32 v111, 0, v111
	v_mul_f32_e32 v96, v96, v96
	v_mul_f32_e32 v97, v97, v97
	v_mul_f32_e32 v98, v98, v98
	v_mul_f32_e32 v99, v99, v99
	v_mul_f32_e32 v100, v100, v100
	v_mul_f32_e32 v101, v101, v101
	v_mul_f32_e32 v102, v102, v102
	v_mul_f32_e32 v103, v103, v103
	v_mul_f32_e32 v104, v104, v104
	v_mul_f32_e32 v105, v105, v105
	v_mul_f32_e32 v106, v106, v106
	v_mul_f32_e32 v107, v107, v107
	v_mul_f32_e32 v108, v108, v108
	v_mul_f32_e32 v109, v109, v109
	v_mul_f32_e32 v110, v110, v110
	v_mul_f32_e32 v111, v111, v111
	v_cvt_pk_bf16_f32 v96, v96, v97
	v_cvt_pk_bf16_f32 v97, v98, v99
	v_cvt_pk_bf16_f32 v98, v100, v101
	v_cvt_pk_bf16_f32 v99, v102, v103
	v_cvt_pk_bf16_f32 v100, v104, v105
	v_cvt_pk_bf16_f32 v101, v106, v107
	v_cvt_pk_bf16_f32 v102, v108, v109
	v_cvt_pk_bf16_f32 v103, v110, v111
	s_nop 1
	v_permlane32_swap_b32_e32 v96, v98
	v_permlane32_swap_b32_e32 v97, v99
	v_permlane32_swap_b32_e32 v100, v102
	v_permlane32_swap_b32_e32 v101, v103
	ds_write_b128 v145, v[96:99]
	ds_write_b128 v146, v[100:103]
	v_mul_f32_e32 v80, v80, v137
	v_mul_f32_e32 v81, v81, v137
	v_mul_f32_e32 v82, v82, v137
	v_mul_f32_e32 v83, v83, v137
	v_mul_f32_e32 v84, v84, v137
	v_mul_f32_e32 v85, v85, v137
	v_mul_f32_e32 v86, v86, v137
	v_mul_f32_e32 v87, v87, v137
	v_mul_f32_e32 v88, v88, v137
	v_mul_f32_e32 v89, v89, v137
	v_mul_f32_e32 v90, v90, v137
	v_mul_f32_e32 v91, v91, v137
	v_mul_f32_e32 v92, v92, v137
	v_mul_f32_e32 v93, v93, v137
	v_mul_f32_e32 v94, v94, v137
	v_mul_f32_e32 v95, v95, v137
	v_max_f32_e32 v80, 0, v80
	v_max_f32_e32 v81, 0, v81
	v_max_f32_e32 v82, 0, v82
	v_max_f32_e32 v83, 0, v83
	v_max_f32_e32 v84, 0, v84
	v_max_f32_e32 v85, 0, v85
	v_max_f32_e32 v86, 0, v86
	v_max_f32_e32 v87, 0, v87
	v_max_f32_e32 v88, 0, v88
	v_max_f32_e32 v89, 0, v89
	v_max_f32_e32 v90, 0, v90
	v_max_f32_e32 v91, 0, v91
	v_max_f32_e32 v92, 0, v92
	v_max_f32_e32 v93, 0, v93
	v_max_f32_e32 v94, 0, v94
	v_max_f32_e32 v95, 0, v95
	v_mul_f32_e32 v80, v80, v80
	v_mul_f32_e32 v81, v81, v81
	v_mul_f32_e32 v82, v82, v82
	v_mul_f32_e32 v83, v83, v83
	v_mul_f32_e32 v84, v84, v84
	v_mul_f32_e32 v85, v85, v85
	v_mul_f32_e32 v86, v86, v86
	v_mul_f32_e32 v87, v87, v87
	v_mul_f32_e32 v88, v88, v88
	v_mul_f32_e32 v89, v89, v89
	v_mul_f32_e32 v90, v90, v90
	v_mul_f32_e32 v91, v91, v91
	v_mul_f32_e32 v92, v92, v92
	v_mul_f32_e32 v93, v93, v93
	v_mul_f32_e32 v94, v94, v94
	v_mul_f32_e32 v95, v95, v95
	v_cvt_pk_bf16_f32 v80, v80, v81
	v_cvt_pk_bf16_f32 v81, v82, v83
	v_cvt_pk_bf16_f32 v82, v84, v85
	v_cvt_pk_bf16_f32 v83, v86, v87
	v_cvt_pk_bf16_f32 v84, v88, v89
	v_cvt_pk_bf16_f32 v85, v90, v91
	v_cvt_pk_bf16_f32 v86, v92, v93
	v_cvt_pk_bf16_f32 v87, v94, v95
	s_nop 1
	v_permlane32_swap_b32_e32 v80, v82
	v_permlane32_swap_b32_e32 v81, v83
	v_permlane32_swap_b32_e32 v84, v86
	v_permlane32_swap_b32_e32 v85, v87
	ds_write_b128 v143, v[80:83] offset:4096
	ds_write_b128 v144, v[84:87] offset:4096
	v_mul_f32_e32 v64, v64, v137
	v_mul_f32_e32 v65, v65, v137
	v_mul_f32_e32 v66, v66, v137
	v_mul_f32_e32 v67, v67, v137
	v_mul_f32_e32 v68, v68, v137
	v_mul_f32_e32 v69, v69, v137
	v_mul_f32_e32 v70, v70, v137
	v_mul_f32_e32 v71, v71, v137
	v_mul_f32_e32 v72, v72, v137
	v_mul_f32_e32 v73, v73, v137
	v_mul_f32_e32 v74, v74, v137
	v_mul_f32_e32 v75, v75, v137
	v_mul_f32_e32 v76, v76, v137
	v_mul_f32_e32 v77, v77, v137
	v_mul_f32_e32 v78, v78, v137
	v_mul_f32_e32 v79, v79, v137
	v_max_f32_e32 v64, 0, v64
	v_max_f32_e32 v65, 0, v65
	v_max_f32_e32 v66, 0, v66
	v_max_f32_e32 v67, 0, v67
	v_max_f32_e32 v68, 0, v68
	v_max_f32_e32 v69, 0, v69
	v_max_f32_e32 v70, 0, v70
	v_max_f32_e32 v71, 0, v71
	v_max_f32_e32 v72, 0, v72
	v_max_f32_e32 v73, 0, v73
	v_max_f32_e32 v74, 0, v74
	v_max_f32_e32 v75, 0, v75
	v_max_f32_e32 v76, 0, v76
	v_max_f32_e32 v77, 0, v77
	v_max_f32_e32 v78, 0, v78
	v_max_f32_e32 v79, 0, v79
	v_mul_f32_e32 v64, v64, v64
	v_mul_f32_e32 v65, v65, v65
	v_mul_f32_e32 v66, v66, v66
	v_mul_f32_e32 v67, v67, v67
	v_mul_f32_e32 v68, v68, v68
	v_mul_f32_e32 v69, v69, v69
	v_mul_f32_e32 v70, v70, v70
	v_mul_f32_e32 v71, v71, v71
	v_mul_f32_e32 v72, v72, v72
	v_mul_f32_e32 v73, v73, v73
	v_mul_f32_e32 v74, v74, v74
	v_mul_f32_e32 v75, v75, v75
	v_mul_f32_e32 v76, v76, v76
	v_mul_f32_e32 v77, v77, v77
	v_mul_f32_e32 v78, v78, v78
	v_mul_f32_e32 v79, v79, v79
	v_cvt_pk_bf16_f32 v64, v64, v65
	v_cvt_pk_bf16_f32 v65, v66, v67
	v_cvt_pk_bf16_f32 v66, v68, v69
	v_cvt_pk_bf16_f32 v67, v70, v71
	v_cvt_pk_bf16_f32 v68, v72, v73
	v_cvt_pk_bf16_f32 v69, v74, v75
	v_cvt_pk_bf16_f32 v70, v76, v77
	v_cvt_pk_bf16_f32 v71, v78, v79
	s_nop 1
	v_permlane32_swap_b32_e32 v64, v66
	v_permlane32_swap_b32_e32 v65, v67
	v_permlane32_swap_b32_e32 v68, v70
	v_permlane32_swap_b32_e32 v69, v71
	ds_write_b128 v145, v[64:67] offset:4096
	ds_write_b128 v146, v[68:71] offset:4096
	ds_read_b128 v[120:123], v133
	ds_read_b128 v[124:127], v133 offset:1024
	ds_read_b128 v[104:107], v133 offset:2048
	ds_read_b128 v[108:111], v133 offset:3072
	ds_read_b128 v[88:91], v133 offset:4096
	ds_read_b128 v[92:95], v133 offset:5120
	ds_read_b128 v[72:75], v133 offset:6144
	ds_read_b128 v[76:79], v133 offset:7168
	s_waitcnt lgkmcnt(7)
	global_store_dwordx4 v[134:135], v[120:123], off
	v_lshl_add_u64 v[134:135], v[134:135], 0, s[36:37]
	s_waitcnt lgkmcnt(6)
	global_store_dwordx4 v[134:135], v[124:127], off
	v_lshl_add_u64 v[134:135], v[134:135], 0, s[36:37]
	s_waitcnt lgkmcnt(5)
	global_store_dwordx4 v[134:135], v[104:107], off
	v_lshl_add_u64 v[134:135], v[134:135], 0, s[36:37]
	s_waitcnt lgkmcnt(4)
	global_store_dwordx4 v[134:135], v[108:111], off
	v_lshl_add_u64 v[134:135], v[134:135], 0, s[36:37]
	s_waitcnt lgkmcnt(3)
	global_store_dwordx4 v[134:135], v[88:91], off
	v_lshl_add_u64 v[134:135], v[134:135], 0, s[36:37]
	s_waitcnt lgkmcnt(2)
	global_store_dwordx4 v[134:135], v[92:95], off
	v_lshl_add_u64 v[134:135], v[134:135], 0, s[36:37]
	s_waitcnt lgkmcnt(1)
	global_store_dwordx4 v[134:135], v[72:75], off
	v_lshl_add_u64 v[134:135], v[134:135], 0, s[36:37]
	s_waitcnt lgkmcnt(0)
	global_store_dwordx4 v[134:135], v[76:79], off
	v_lshl_add_u64 v[134:135], v[134:135], 0, s[36:37]
	v_mul_f32_e32 v48, v48, v138
	v_mul_f32_e32 v49, v49, v138
	v_mul_f32_e32 v50, v50, v138
	v_mul_f32_e32 v51, v51, v138
	v_mul_f32_e32 v52, v52, v138
	v_mul_f32_e32 v53, v53, v138
	v_mul_f32_e32 v54, v54, v138
	v_mul_f32_e32 v55, v55, v138
	v_mul_f32_e32 v56, v56, v138
	v_mul_f32_e32 v57, v57, v138
	v_mul_f32_e32 v58, v58, v138
	v_mul_f32_e32 v59, v59, v138
	v_mul_f32_e32 v60, v60, v138
	v_mul_f32_e32 v61, v61, v138
	v_mul_f32_e32 v62, v62, v138
	v_mul_f32_e32 v63, v63, v138
	v_max_f32_e32 v48, 0, v48
	v_max_f32_e32 v49, 0, v49
	v_max_f32_e32 v50, 0, v50
	v_max_f32_e32 v51, 0, v51
	v_max_f32_e32 v52, 0, v52
	v_max_f32_e32 v53, 0, v53
	v_max_f32_e32 v54, 0, v54
	v_max_f32_e32 v55, 0, v55
	v_max_f32_e32 v56, 0, v56
	v_max_f32_e32 v57, 0, v57
	v_max_f32_e32 v58, 0, v58
	v_max_f32_e32 v59, 0, v59
	v_max_f32_e32 v60, 0, v60
	v_max_f32_e32 v61, 0, v61
	v_max_f32_e32 v62, 0, v62
	v_max_f32_e32 v63, 0, v63
	v_mul_f32_e32 v48, v48, v48
	v_mul_f32_e32 v49, v49, v49
	v_mul_f32_e32 v50, v50, v50
	v_mul_f32_e32 v51, v51, v51
	v_mul_f32_e32 v52, v52, v52
	v_mul_f32_e32 v53, v53, v53
	v_mul_f32_e32 v54, v54, v54
	v_mul_f32_e32 v55, v55, v55
	v_mul_f32_e32 v56, v56, v56
	v_mul_f32_e32 v57, v57, v57
	v_mul_f32_e32 v58, v58, v58
	v_mul_f32_e32 v59, v59, v59
	v_mul_f32_e32 v60, v60, v60
	v_mul_f32_e32 v61, v61, v61
	v_mul_f32_e32 v62, v62, v62
	v_mul_f32_e32 v63, v63, v63
	v_cvt_pk_bf16_f32 v48, v48, v49
	v_cvt_pk_bf16_f32 v49, v50, v51
	v_cvt_pk_bf16_f32 v50, v52, v53
	v_cvt_pk_bf16_f32 v51, v54, v55
	v_cvt_pk_bf16_f32 v52, v56, v57
	v_cvt_pk_bf16_f32 v53, v58, v59
	v_cvt_pk_bf16_f32 v54, v60, v61
	v_cvt_pk_bf16_f32 v55, v62, v63
	s_nop 1
	v_permlane32_swap_b32_e32 v48, v50
	v_permlane32_swap_b32_e32 v49, v51
	v_permlane32_swap_b32_e32 v52, v54
	v_permlane32_swap_b32_e32 v53, v55
	ds_write_b128 v143, v[48:51]
	ds_write_b128 v144, v[52:55]
	v_mul_f32_e32 v32, v32, v138
	v_mul_f32_e32 v33, v33, v138
	v_mul_f32_e32 v34, v34, v138
	v_mul_f32_e32 v35, v35, v138
	v_mul_f32_e32 v36, v36, v138
	v_mul_f32_e32 v37, v37, v138
	v_mul_f32_e32 v38, v38, v138
	v_mul_f32_e32 v39, v39, v138
	v_mul_f32_e32 v40, v40, v138
	v_mul_f32_e32 v41, v41, v138
	v_mul_f32_e32 v42, v42, v138
	v_mul_f32_e32 v43, v43, v138
	v_mul_f32_e32 v44, v44, v138
	v_mul_f32_e32 v45, v45, v138
	v_mul_f32_e32 v46, v46, v138
	v_mul_f32_e32 v47, v47, v138
	v_max_f32_e32 v32, 0, v32
	v_max_f32_e32 v33, 0, v33
	v_max_f32_e32 v34, 0, v34
	v_max_f32_e32 v35, 0, v35
	v_max_f32_e32 v36, 0, v36
	v_max_f32_e32 v37, 0, v37
	v_max_f32_e32 v38, 0, v38
	v_max_f32_e32 v39, 0, v39
	v_max_f32_e32 v40, 0, v40
	v_max_f32_e32 v41, 0, v41
	v_max_f32_e32 v42, 0, v42
	v_max_f32_e32 v43, 0, v43
	v_max_f32_e32 v44, 0, v44
	v_max_f32_e32 v45, 0, v45
	v_max_f32_e32 v46, 0, v46
	v_max_f32_e32 v47, 0, v47
	v_mul_f32_e32 v32, v32, v32
	v_mul_f32_e32 v33, v33, v33
	v_mul_f32_e32 v34, v34, v34
	v_mul_f32_e32 v35, v35, v35
	v_mul_f32_e32 v36, v36, v36
	v_mul_f32_e32 v37, v37, v37
	v_mul_f32_e32 v38, v38, v38
	v_mul_f32_e32 v39, v39, v39
	v_mul_f32_e32 v40, v40, v40
	v_mul_f32_e32 v41, v41, v41
	v_mul_f32_e32 v42, v42, v42
	v_mul_f32_e32 v43, v43, v43
	v_mul_f32_e32 v44, v44, v44
	v_mul_f32_e32 v45, v45, v45
	v_mul_f32_e32 v46, v46, v46
	v_mul_f32_e32 v47, v47, v47
	v_cvt_pk_bf16_f32 v32, v32, v33
	v_cvt_pk_bf16_f32 v33, v34, v35
	v_cvt_pk_bf16_f32 v34, v36, v37
	v_cvt_pk_bf16_f32 v35, v38, v39
	v_cvt_pk_bf16_f32 v36, v40, v41
	v_cvt_pk_bf16_f32 v37, v42, v43
	v_cvt_pk_bf16_f32 v38, v44, v45
	v_cvt_pk_bf16_f32 v39, v46, v47
	s_nop 1
	v_permlane32_swap_b32_e32 v32, v34
	v_permlane32_swap_b32_e32 v33, v35
	v_permlane32_swap_b32_e32 v36, v38
	v_permlane32_swap_b32_e32 v37, v39
	ds_write_b128 v145, v[32:35]
	ds_write_b128 v146, v[36:39]
	v_mul_f32_e32 v16, v16, v139
	v_mul_f32_e32 v17, v17, v139
	v_mul_f32_e32 v18, v18, v139
	v_mul_f32_e32 v19, v19, v139
	v_mul_f32_e32 v20, v20, v139
	v_mul_f32_e32 v21, v21, v139
	v_mul_f32_e32 v22, v22, v139
	v_mul_f32_e32 v23, v23, v139
	v_mul_f32_e32 v24, v24, v139
	v_mul_f32_e32 v25, v25, v139
	v_mul_f32_e32 v26, v26, v139
	v_mul_f32_e32 v27, v27, v139
	v_mul_f32_e32 v28, v28, v139
	v_mul_f32_e32 v29, v29, v139
	v_mul_f32_e32 v30, v30, v139
	v_mul_f32_e32 v31, v31, v139
	v_max_f32_e32 v16, 0, v16
	v_max_f32_e32 v17, 0, v17
	v_max_f32_e32 v18, 0, v18
	v_max_f32_e32 v19, 0, v19
	v_max_f32_e32 v20, 0, v20
	v_max_f32_e32 v21, 0, v21
	v_max_f32_e32 v22, 0, v22
	v_max_f32_e32 v23, 0, v23
	v_max_f32_e32 v24, 0, v24
	v_max_f32_e32 v25, 0, v25
	v_max_f32_e32 v26, 0, v26
	v_max_f32_e32 v27, 0, v27
	v_max_f32_e32 v28, 0, v28
	v_max_f32_e32 v29, 0, v29
	v_max_f32_e32 v30, 0, v30
	v_max_f32_e32 v31, 0, v31
	v_mul_f32_e32 v16, v16, v16
	v_mul_f32_e32 v17, v17, v17
	v_mul_f32_e32 v18, v18, v18
	v_mul_f32_e32 v19, v19, v19
	v_mul_f32_e32 v20, v20, v20
	v_mul_f32_e32 v21, v21, v21
	v_mul_f32_e32 v22, v22, v22
	v_mul_f32_e32 v23, v23, v23
	v_mul_f32_e32 v24, v24, v24
	v_mul_f32_e32 v25, v25, v25
	v_mul_f32_e32 v26, v26, v26
	v_mul_f32_e32 v27, v27, v27
	v_mul_f32_e32 v28, v28, v28
	v_mul_f32_e32 v29, v29, v29
	v_mul_f32_e32 v30, v30, v30
	v_mul_f32_e32 v31, v31, v31
	v_cvt_pk_bf16_f32 v16, v16, v17
	v_cvt_pk_bf16_f32 v17, v18, v19
	v_cvt_pk_bf16_f32 v18, v20, v21
	v_cvt_pk_bf16_f32 v19, v22, v23
	v_cvt_pk_bf16_f32 v20, v24, v25
	v_cvt_pk_bf16_f32 v21, v26, v27
	v_cvt_pk_bf16_f32 v22, v28, v29
	v_cvt_pk_bf16_f32 v23, v30, v31
	s_nop 1
	v_permlane32_swap_b32_e32 v16, v18
	v_permlane32_swap_b32_e32 v17, v19
	v_permlane32_swap_b32_e32 v20, v22
	v_permlane32_swap_b32_e32 v21, v23
	ds_write_b128 v143, v[16:19] offset:4096
	ds_write_b128 v144, v[20:23] offset:4096
	v_mul_f32_e32 v0, v0, v139
	v_mul_f32_e32 v1, v1, v139
	v_mul_f32_e32 v2, v2, v139
	v_mul_f32_e32 v3, v3, v139
	v_mul_f32_e32 v4, v4, v139
	v_mul_f32_e32 v5, v5, v139
	v_mul_f32_e32 v6, v6, v139
	v_mul_f32_e32 v7, v7, v139
	v_mul_f32_e32 v8, v8, v139
	v_mul_f32_e32 v9, v9, v139
	v_mul_f32_e32 v10, v10, v139
	v_mul_f32_e32 v11, v11, v139
	v_mul_f32_e32 v12, v12, v139
	v_mul_f32_e32 v13, v13, v139
	v_mul_f32_e32 v14, v14, v139
	v_mul_f32_e32 v15, v15, v139
	v_max_f32_e32 v0, 0, v0
	v_max_f32_e32 v1, 0, v1
	v_max_f32_e32 v2, 0, v2
	v_max_f32_e32 v3, 0, v3
	v_max_f32_e32 v4, 0, v4
	v_max_f32_e32 v5, 0, v5
	v_max_f32_e32 v6, 0, v6
	v_max_f32_e32 v7, 0, v7
	v_max_f32_e32 v8, 0, v8
	v_max_f32_e32 v9, 0, v9
	v_max_f32_e32 v10, 0, v10
	v_max_f32_e32 v11, 0, v11
	v_max_f32_e32 v12, 0, v12
	v_max_f32_e32 v13, 0, v13
	v_max_f32_e32 v14, 0, v14
	v_max_f32_e32 v15, 0, v15
	v_mul_f32_e32 v0, v0, v0
	v_mul_f32_e32 v1, v1, v1
	v_mul_f32_e32 v2, v2, v2
	v_mul_f32_e32 v3, v3, v3
	v_mul_f32_e32 v4, v4, v4
	v_mul_f32_e32 v5, v5, v5
	v_mul_f32_e32 v6, v6, v6
	v_mul_f32_e32 v7, v7, v7
	v_mul_f32_e32 v8, v8, v8
	v_mul_f32_e32 v9, v9, v9
	v_mul_f32_e32 v10, v10, v10
	v_mul_f32_e32 v11, v11, v11
	v_mul_f32_e32 v12, v12, v12
	v_mul_f32_e32 v13, v13, v13
	v_mul_f32_e32 v14, v14, v14
	v_mul_f32_e32 v15, v15, v15
	v_cvt_pk_bf16_f32 v0, v0, v1
	v_cvt_pk_bf16_f32 v1, v2, v3
	v_cvt_pk_bf16_f32 v2, v4, v5
	v_cvt_pk_bf16_f32 v3, v6, v7
	v_cvt_pk_bf16_f32 v4, v8, v9
	v_cvt_pk_bf16_f32 v5, v10, v11
	v_cvt_pk_bf16_f32 v6, v12, v13
	v_cvt_pk_bf16_f32 v7, v14, v15
	s_nop 1
	v_permlane32_swap_b32_e32 v0, v2
	v_permlane32_swap_b32_e32 v1, v3
	v_permlane32_swap_b32_e32 v4, v6
	v_permlane32_swap_b32_e32 v5, v7
	ds_write_b128 v145, v[0:3] offset:4096
	ds_write_b128 v146, v[4:7] offset:4096
	ds_read_b128 v[56:59], v133
	ds_read_b128 v[60:63], v133 offset:1024
	ds_read_b128 v[40:43], v133 offset:2048
	ds_read_b128 v[44:47], v133 offset:3072
	ds_read_b128 v[24:27], v133 offset:4096
	ds_read_b128 v[28:31], v133 offset:5120
	ds_read_b128 v[8:11], v133 offset:6144
	ds_read_b128 v[12:15], v133 offset:7168
	s_waitcnt lgkmcnt(7)
	global_store_dwordx4 v[134:135], v[56:59], off
	v_lshl_add_u64 v[134:135], v[134:135], 0, s[36:37]
	s_waitcnt lgkmcnt(6)
	global_store_dwordx4 v[134:135], v[60:63], off
	v_lshl_add_u64 v[134:135], v[134:135], 0, s[36:37]
	s_waitcnt lgkmcnt(5)
	global_store_dwordx4 v[134:135], v[40:43], off
	v_lshl_add_u64 v[134:135], v[134:135], 0, s[36:37]
	s_waitcnt lgkmcnt(4)
	global_store_dwordx4 v[134:135], v[44:47], off
	v_lshl_add_u64 v[134:135], v[134:135], 0, s[36:37]
	s_waitcnt lgkmcnt(3)
	global_store_dwordx4 v[134:135], v[24:27], off
	v_lshl_add_u64 v[134:135], v[134:135], 0, s[36:37]
	s_waitcnt lgkmcnt(2)
	global_store_dwordx4 v[134:135], v[28:31], off
	v_lshl_add_u64 v[134:135], v[134:135], 0, s[36:37]
	s_waitcnt lgkmcnt(1)
	global_store_dwordx4 v[134:135], v[8:11], off
	v_lshl_add_u64 v[134:135], v[134:135], 0, s[36:37]
	s_waitcnt lgkmcnt(0)
	global_store_dwordx4 v[134:135], v[12:15], off
	v_lshl_add_u64 v[134:135], v[134:135], 0, s[36:37]
	s_and_b64 vcc, exec, s[2:3]
	s_waitcnt vmcnt(63) expcnt(7) lgkmcnt(15)
	s_barrier
	s_cbranch_vccnz .LBB0_709
